# v50 with sgemm_wide K loops staged through wave-private LDS by LDS-DMA (coalesced 8-row x 128-B pieces, ds_read_b128 into MFMA layout)
# speedup vs baseline: 1.0091x; 1.0089x over previous
.LBB0_309:
	s_and_b32 s9, s5, 0xffffffc0
	v_add_u32_e32 v0, s9, v33
	v_ashrrev_i32_e32 v1, 31, v0
	s_lshl_b32 s9, s4, 11
	v_lshlrev_b64 v[0:1], 11, v[0:1]
	s_and_b32 s9, s9, 0x7c0000
	v_lshl_add_u64 v[20:21], s[88:89], 0, v[0:1]
	v_lshl_or_b32 v148, v34, 11, s9
	v_mov_b32_e32 v0, 0
	v_lshl_add_u64 v[22:23], s[2:3], 0, v[148:149]
	s_movk_i32 s9, 0xffe0
	v_mov_b32_e32 v1, v0
	v_mov_b32_e32 v2, v0
	v_mov_b32_e32 v3, v0
	v_mov_b32_e32 v4, v0
	v_mov_b32_e32 v5, v0
	v_mov_b32_e32 v6, v0
	v_mov_b32_e32 v7, v0
	v_mov_b32_e32 v8, v0
	v_mov_b32_e32 v9, v0
	v_mov_b32_e32 v10, v0
	v_mov_b32_e32 v11, v0
	v_mov_b32_e32 v12, v0
	v_mov_b32_e32 v13, v0
	v_mov_b32_e32 v14, v0
	v_mov_b32_e32 v15, v0
	v_lshl_add_u64 v[24:25], v[20:21], 0, v[18:19]
	v_add_co_u32_e32 v30, vcc, s7, v24
	s_nop 1
	v_addc_co_u32_e32 v31, vcc, 0, v25, vcc
	v_add_co_u32_e32 v24, vcc, s30, v24
	s_nop 1
	v_addc_co_u32_e32 v25, vcc, 0, v25, vcc
	v_lshl_add_u64 v[26:27], v[22:23], 0, v[18:19]
	s_mov_b32 s10, 0x8000
	v_add_co_u32_e32 v28, vcc, s10, v26
	s_nop 1
	v_addc_co_u32_e32 v29, vcc, 0, v27, vcc
	v_and_b32_e32 v113, 63, v176
	v_lshrrev_b32_e32 v114, 3, v113
	v_and_b32_e32 v115, 15, v113
	v_sub_u32_e32 v114, v114, v115
	v_and_b32_e32 v116, 7, v113
	v_lshrrev_b32_e32 v117, 4, v113
	v_sub_u32_e32 v116, v116, v117
	v_lshlrev_b32_e32 v114, 11, v114
	v_lshl_add_u32 v110, v116, 4, v114
	v_ashrrev_i32_e32 v111, 31, v110
	v_lshl_add_u64 v[94:95], v[30:31], 0, v[110:111]
	s_nop 0
	v_add_co_u32_e32 v96, vcc, 0x4000, v94
	s_nop 1
	v_addc_co_u32_e32 v97, vcc, 0, v95, vcc
	v_lshl_add_u64 v[98:99], v[26:27], 0, v[110:111]
	s_nop 0
	v_add_co_u32_e32 v100, vcc, 0x4000, v98
	s_nop 1
	v_addc_co_u32_e32 v101, vcc, 0, v99, vcc
	v_lshl_add_u64 v[102:103], v[28:29], 0, v[110:111]
	s_nop 0
	v_add_co_u32_e32 v104, vcc, 0x4000, v102
	s_nop 1
	v_addc_co_u32_e32 v105, vcc, 0, v103, vcc
	v_lshl_add_u64 v[106:107], v[24:25], 0, v[110:111]
	s_nop 0
	v_add_co_u32_e32 v108, vcc, 0x4000, v106
	s_nop 1
	v_addc_co_u32_e32 v109, vcc, 0, v107, vcc
	v_lshrrev_b32_e32 v114, 3, v115
	v_and_b32_e32 v116, 7, v115
	v_lshlrev_b32_e32 v114, 10, v114
	v_lshl_add_u32 v114, v116, 7, v114
	v_lshl_add_u32 v112, v117, 4, v114
	v_lshrrev_b32_e32 v113, 6, v176
	s_nop 1
	v_readfirstlane_b32 s100, v113
	s_nop 3
	s_lshl_b32 s100, s100, 14
	s_add_i32 s100, s100, 0x800
	s_nop 0
	v_add_u32_e32 v112, s100, v112
	s_add_i32 m0, s100, 0
	s_nop 0
	global_load_lds_dwordx4 v[94:95], off
	s_add_i32 m0, s100, 1024
	s_nop 0
	global_load_lds_dwordx4 v[96:97], off
	s_add_i32 m0, s100, 2048
	s_nop 0
	global_load_lds_dwordx4 v[98:99], off
	s_add_i32 m0, s100, 3072
	s_nop 0
	global_load_lds_dwordx4 v[100:101], off
	s_add_i32 m0, s100, 4096
	s_nop 0
	global_load_lds_dwordx4 v[102:103], off
	s_add_i32 m0, s100, 5120
	s_nop 0
	global_load_lds_dwordx4 v[104:105], off
	s_add_i32 m0, s100, 6144
	s_nop 0
	global_load_lds_dwordx4 v[106:107], off
	s_add_i32 m0, s100, 7168
	s_nop 0
	global_load_lds_dwordx4 v[108:109], off
	s_add_i32 m0, s100, 8064
	s_nop 0
	global_load_lds_dwordx4 v[94:95], off offset:128
	s_add_i32 m0, s100, 9088
	s_nop 0
	global_load_lds_dwordx4 v[96:97], off offset:128
	s_add_i32 m0, s100, 10112
	s_nop 0
	global_load_lds_dwordx4 v[98:99], off offset:128
	s_add_i32 m0, s100, 11136
	s_nop 0
	global_load_lds_dwordx4 v[100:101], off offset:128
	s_add_i32 m0, s100, 12160
	s_nop 0
	global_load_lds_dwordx4 v[102:103], off offset:128
	s_add_i32 m0, s100, 13184
	s_nop 0
	global_load_lds_dwordx4 v[104:105], off offset:128
	s_add_i32 m0, s100, 14208
	s_nop 0
	global_load_lds_dwordx4 v[106:107], off offset:128
	s_add_i32 m0, s100, 15232
	s_nop 0
	global_load_lds_dwordx4 v[108:109], off offset:128
	s_waitcnt vmcnt(8)
	ds_read_b128 v[62:65], v112
	ds_read_b128 v[66:69], v112 offset:64
	ds_read_b128 v[70:73], v112 offset:2048
	ds_read_b128 v[74:77], v112 offset:2112
	ds_read_b128 v[78:81], v112 offset:4096
	ds_read_b128 v[82:85], v112 offset:4160
	ds_read_b128 v[86:89], v112 offset:6144
	ds_read_b128 v[90:93], v112 offset:6208
	s_waitcnt lgkmcnt(0)
	s_add_i32 m0, s100, -256
	s_nop 0
	global_load_lds_dwordx4 v[94:95], off offset:256
	s_add_i32 m0, s100, 768
	s_nop 0
	global_load_lds_dwordx4 v[96:97], off offset:256
	s_add_i32 m0, s100, 1792
	s_nop 0
	global_load_lds_dwordx4 v[98:99], off offset:256
	s_add_i32 m0, s100, 2816
	s_nop 0
	global_load_lds_dwordx4 v[100:101], off offset:256
	s_add_i32 m0, s100, 3840
	s_nop 0
	global_load_lds_dwordx4 v[102:103], off offset:256
	s_add_i32 m0, s100, 4864
	s_nop 0
	global_load_lds_dwordx4 v[104:105], off offset:256
	s_add_i32 m0, s100, 5888
	s_nop 0
	global_load_lds_dwordx4 v[106:107], off offset:256
	s_add_i32 m0, s100, 6912
	s_nop 0
	global_load_lds_dwordx4 v[108:109], off offset:256
	v_mfma_f32_16x16x32_bf16 v[12:15], v[70:73], v[62:65], v[12:15]
	v_mfma_f32_16x16x32_bf16 v[8:11], v[78:81], v[62:65], v[8:11]
	v_mfma_f32_16x16x32_bf16 v[4:7], v[70:73], v[86:89], v[4:7]
	v_mfma_f32_16x16x32_bf16 v[0:3], v[78:81], v[86:89], v[0:3]
	v_mfma_f32_16x16x32_bf16 v[12:15], v[74:77], v[66:69], v[12:15]
	v_mfma_f32_16x16x32_bf16 v[8:11], v[82:85], v[66:69], v[8:11]
	v_mfma_f32_16x16x32_bf16 v[4:7], v[74:77], v[90:93], v[4:7]
	v_mfma_f32_16x16x32_bf16 v[0:3], v[82:85], v[90:93], v[0:3]
	s_waitcnt vmcnt(8)
	ds_read_b128 v[62:65], v112 offset:8192
	ds_read_b128 v[66:69], v112 offset:8256
	ds_read_b128 v[70:73], v112 offset:10240
	ds_read_b128 v[74:77], v112 offset:10304
	ds_read_b128 v[78:81], v112 offset:12288
	ds_read_b128 v[82:85], v112 offset:12352
	ds_read_b128 v[86:89], v112 offset:14336
	ds_read_b128 v[90:93], v112 offset:14400
	s_waitcnt lgkmcnt(0)
	s_add_i32 m0, s100, 7808
	s_nop 0
	global_load_lds_dwordx4 v[94:95], off offset:384
	s_add_i32 m0, s100, 8832
	s_nop 0
	global_load_lds_dwordx4 v[96:97], off offset:384
	s_add_i32 m0, s100, 9856
	s_nop 0
	global_load_lds_dwordx4 v[98:99], off offset:384
	s_add_i32 m0, s100, 10880
	s_nop 0
	global_load_lds_dwordx4 v[100:101], off offset:384
	s_add_i32 m0, s100, 11904
	s_nop 0
	global_load_lds_dwordx4 v[102:103], off offset:384
	s_add_i32 m0, s100, 12928
	s_nop 0
	global_load_lds_dwordx4 v[104:105], off offset:384
	s_add_i32 m0, s100, 13952
	s_nop 0
	global_load_lds_dwordx4 v[106:107], off offset:384
	s_add_i32 m0, s100, 14976
	s_nop 0
	global_load_lds_dwordx4 v[108:109], off offset:384
	v_mfma_f32_16x16x32_bf16 v[12:15], v[70:73], v[62:65], v[12:15]
	v_mfma_f32_16x16x32_bf16 v[8:11], v[78:81], v[62:65], v[8:11]
	v_mfma_f32_16x16x32_bf16 v[4:7], v[70:73], v[86:89], v[4:7]
	v_mfma_f32_16x16x32_bf16 v[0:3], v[78:81], v[86:89], v[0:3]
	v_mfma_f32_16x16x32_bf16 v[12:15], v[74:77], v[66:69], v[12:15]
	v_mfma_f32_16x16x32_bf16 v[8:11], v[82:85], v[66:69], v[8:11]
	v_mfma_f32_16x16x32_bf16 v[4:7], v[74:77], v[90:93], v[4:7]
	v_mfma_f32_16x16x32_bf16 v[0:3], v[82:85], v[90:93], v[0:3]
	s_waitcnt vmcnt(8)
	ds_read_b128 v[62:65], v112
	ds_read_b128 v[66:69], v112 offset:64
	ds_read_b128 v[70:73], v112 offset:2048
	ds_read_b128 v[74:77], v112 offset:2112
	ds_read_b128 v[78:81], v112 offset:4096
	ds_read_b128 v[82:85], v112 offset:4160
	ds_read_b128 v[86:89], v112 offset:6144
	ds_read_b128 v[90:93], v112 offset:6208
	s_waitcnt lgkmcnt(0)
	s_add_i32 m0, s100, -512
	s_nop 0
	global_load_lds_dwordx4 v[94:95], off offset:512
	s_add_i32 m0, s100, 512
	s_nop 0
	global_load_lds_dwordx4 v[96:97], off offset:512
	s_add_i32 m0, s100, 1536
	s_nop 0
	global_load_lds_dwordx4 v[98:99], off offset:512
	s_add_i32 m0, s100, 2560
	s_nop 0
	global_load_lds_dwordx4 v[100:101], off offset:512
	s_add_i32 m0, s100, 3584
	s_nop 0
	global_load_lds_dwordx4 v[102:103], off offset:512
	s_add_i32 m0, s100, 4608
	s_nop 0
	global_load_lds_dwordx4 v[104:105], off offset:512
	s_add_i32 m0, s100, 5632
	s_nop 0
	global_load_lds_dwordx4 v[106:107], off offset:512
	s_add_i32 m0, s100, 6656
	s_nop 0
	global_load_lds_dwordx4 v[108:109], off offset:512
	v_mfma_f32_16x16x32_bf16 v[12:15], v[70:73], v[62:65], v[12:15]
	v_mfma_f32_16x16x32_bf16 v[8:11], v[78:81], v[62:65], v[8:11]
	v_mfma_f32_16x16x32_bf16 v[4:7], v[70:73], v[86:89], v[4:7]
	v_mfma_f32_16x16x32_bf16 v[0:3], v[78:81], v[86:89], v[0:3]
	v_mfma_f32_16x16x32_bf16 v[12:15], v[74:77], v[66:69], v[12:15]
	v_mfma_f32_16x16x32_bf16 v[8:11], v[82:85], v[66:69], v[8:11]
	v_mfma_f32_16x16x32_bf16 v[4:7], v[74:77], v[90:93], v[4:7]
	v_mfma_f32_16x16x32_bf16 v[0:3], v[82:85], v[90:93], v[0:3]
	s_waitcnt vmcnt(8)
	ds_read_b128 v[62:65], v112 offset:8192
	ds_read_b128 v[66:69], v112 offset:8256
	ds_read_b128 v[70:73], v112 offset:10240
	ds_read_b128 v[74:77], v112 offset:10304
	ds_read_b128 v[78:81], v112 offset:12288
	ds_read_b128 v[82:85], v112 offset:12352
	ds_read_b128 v[86:89], v112 offset:14336
	ds_read_b128 v[90:93], v112 offset:14400
	s_waitcnt lgkmcnt(0)
	s_add_i32 m0, s100, 7552
	s_nop 0
	global_load_lds_dwordx4 v[94:95], off offset:640
	s_add_i32 m0, s100, 8576
	s_nop 0
	global_load_lds_dwordx4 v[96:97], off offset:640
	s_add_i32 m0, s100, 9600
	s_nop 0
	global_load_lds_dwordx4 v[98:99], off offset:640
	s_add_i32 m0, s100, 10624
	s_nop 0
	global_load_lds_dwordx4 v[100:101], off offset:640
	s_add_i32 m0, s100, 11648
	s_nop 0
	global_load_lds_dwordx4 v[102:103], off offset:640
	s_add_i32 m0, s100, 12672
	s_nop 0
	global_load_lds_dwordx4 v[104:105], off offset:640
	s_add_i32 m0, s100, 13696
	s_nop 0
	global_load_lds_dwordx4 v[106:107], off offset:640
	s_add_i32 m0, s100, 14720
	s_nop 0
	global_load_lds_dwordx4 v[108:109], off offset:640
	v_mfma_f32_16x16x32_bf16 v[12:15], v[70:73], v[62:65], v[12:15]
	v_mfma_f32_16x16x32_bf16 v[8:11], v[78:81], v[62:65], v[8:11]
	v_mfma_f32_16x16x32_bf16 v[4:7], v[70:73], v[86:89], v[4:7]
	v_mfma_f32_16x16x32_bf16 v[0:3], v[78:81], v[86:89], v[0:3]
	v_mfma_f32_16x16x32_bf16 v[12:15], v[74:77], v[66:69], v[12:15]
	v_mfma_f32_16x16x32_bf16 v[8:11], v[82:85], v[66:69], v[8:11]
	v_mfma_f32_16x16x32_bf16 v[4:7], v[74:77], v[90:93], v[4:7]
	v_mfma_f32_16x16x32_bf16 v[0:3], v[82:85], v[90:93], v[0:3]
	s_waitcnt vmcnt(8)
	ds_read_b128 v[62:65], v112
	ds_read_b128 v[66:69], v112 offset:64
	ds_read_b128 v[70:73], v112 offset:2048
	ds_read_b128 v[74:77], v112 offset:2112
	ds_read_b128 v[78:81], v112 offset:4096
	ds_read_b128 v[82:85], v112 offset:4160
	ds_read_b128 v[86:89], v112 offset:6144
	ds_read_b128 v[90:93], v112 offset:6208
	s_waitcnt lgkmcnt(0)
	s_add_i32 m0, s100, -768
	s_nop 0
	global_load_lds_dwordx4 v[94:95], off offset:768
	s_add_i32 m0, s100, 256
	s_nop 0
	global_load_lds_dwordx4 v[96:97], off offset:768
	s_add_i32 m0, s100, 1280
	s_nop 0
	global_load_lds_dwordx4 v[98:99], off offset:768
	s_add_i32 m0, s100, 2304
	s_nop 0
	global_load_lds_dwordx4 v[100:101], off offset:768
	s_add_i32 m0, s100, 3328
	s_nop 0
	global_load_lds_dwordx4 v[102:103], off offset:768
	s_add_i32 m0, s100, 4352
	s_nop 0
	global_load_lds_dwordx4 v[104:105], off offset:768
	s_add_i32 m0, s100, 5376
	s_nop 0
	global_load_lds_dwordx4 v[106:107], off offset:768
	s_add_i32 m0, s100, 6400
	s_nop 0
	global_load_lds_dwordx4 v[108:109], off offset:768
	v_mfma_f32_16x16x32_bf16 v[12:15], v[70:73], v[62:65], v[12:15]
	v_mfma_f32_16x16x32_bf16 v[8:11], v[78:81], v[62:65], v[8:11]
	v_mfma_f32_16x16x32_bf16 v[4:7], v[70:73], v[86:89], v[4:7]
	v_mfma_f32_16x16x32_bf16 v[0:3], v[78:81], v[86:89], v[0:3]
	v_mfma_f32_16x16x32_bf16 v[12:15], v[74:77], v[66:69], v[12:15]
	v_mfma_f32_16x16x32_bf16 v[8:11], v[82:85], v[66:69], v[8:11]
	v_mfma_f32_16x16x32_bf16 v[4:7], v[74:77], v[90:93], v[4:7]
	v_mfma_f32_16x16x32_bf16 v[0:3], v[82:85], v[90:93], v[0:3]
	s_waitcnt vmcnt(8)
	ds_read_b128 v[62:65], v112 offset:8192
	ds_read_b128 v[66:69], v112 offset:8256
	ds_read_b128 v[70:73], v112 offset:10240
	ds_read_b128 v[74:77], v112 offset:10304
	ds_read_b128 v[78:81], v112 offset:12288
	ds_read_b128 v[82:85], v112 offset:12352
	ds_read_b128 v[86:89], v112 offset:14336
	ds_read_b128 v[90:93], v112 offset:14400
	s_waitcnt lgkmcnt(0)
	s_add_i32 m0, s100, 7296
	s_nop 0
	global_load_lds_dwordx4 v[94:95], off offset:896
	s_add_i32 m0, s100, 8320
	s_nop 0
	global_load_lds_dwordx4 v[96:97], off offset:896
	s_add_i32 m0, s100, 9344
	s_nop 0
	global_load_lds_dwordx4 v[98:99], off offset:896
	s_add_i32 m0, s100, 10368
	s_nop 0
	global_load_lds_dwordx4 v[100:101], off offset:896
	s_add_i32 m0, s100, 11392
	s_nop 0
	global_load_lds_dwordx4 v[102:103], off offset:896
	s_add_i32 m0, s100, 12416
	s_nop 0
	global_load_lds_dwordx4 v[104:105], off offset:896
	s_add_i32 m0, s100, 13440
	s_nop 0
	global_load_lds_dwordx4 v[106:107], off offset:896
	s_add_i32 m0, s100, 14464
	s_nop 0
	global_load_lds_dwordx4 v[108:109], off offset:896
	v_mfma_f32_16x16x32_bf16 v[12:15], v[70:73], v[62:65], v[12:15]
	v_mfma_f32_16x16x32_bf16 v[8:11], v[78:81], v[62:65], v[8:11]
	v_mfma_f32_16x16x32_bf16 v[4:7], v[70:73], v[86:89], v[4:7]
	v_mfma_f32_16x16x32_bf16 v[0:3], v[78:81], v[86:89], v[0:3]
	v_mfma_f32_16x16x32_bf16 v[12:15], v[74:77], v[66:69], v[12:15]
	v_mfma_f32_16x16x32_bf16 v[8:11], v[82:85], v[66:69], v[8:11]
	v_mfma_f32_16x16x32_bf16 v[4:7], v[74:77], v[90:93], v[4:7]
	v_mfma_f32_16x16x32_bf16 v[0:3], v[82:85], v[90:93], v[0:3]
	s_waitcnt vmcnt(8)
	ds_read_b128 v[62:65], v112
	ds_read_b128 v[66:69], v112 offset:64
	ds_read_b128 v[70:73], v112 offset:2048
	ds_read_b128 v[74:77], v112 offset:2112
	ds_read_b128 v[78:81], v112 offset:4096
	ds_read_b128 v[82:85], v112 offset:4160
	ds_read_b128 v[86:89], v112 offset:6144
	ds_read_b128 v[90:93], v112 offset:6208
	s_waitcnt lgkmcnt(0)
	s_add_i32 m0, s100, -1024
	s_nop 0
	global_load_lds_dwordx4 v[94:95], off offset:1024
	s_add_i32 m0, s100, 0
	s_nop 0
	global_load_lds_dwordx4 v[96:97], off offset:1024
	s_add_i32 m0, s100, 1024
	s_nop 0
	global_load_lds_dwordx4 v[98:99], off offset:1024
	s_add_i32 m0, s100, 2048
	s_nop 0
	global_load_lds_dwordx4 v[100:101], off offset:1024
	s_add_i32 m0, s100, 3072
	s_nop 0
	global_load_lds_dwordx4 v[102:103], off offset:1024
	s_add_i32 m0, s100, 4096
	s_nop 0
	global_load_lds_dwordx4 v[104:105], off offset:1024
	s_add_i32 m0, s100, 5120
	s_nop 0
	global_load_lds_dwordx4 v[106:107], off offset:1024
	s_add_i32 m0, s100, 6144
	s_nop 0
	global_load_lds_dwordx4 v[108:109], off offset:1024
	v_mfma_f32_16x16x32_bf16 v[12:15], v[70:73], v[62:65], v[12:15]
	v_mfma_f32_16x16x32_bf16 v[8:11], v[78:81], v[62:65], v[8:11]
	v_mfma_f32_16x16x32_bf16 v[4:7], v[70:73], v[86:89], v[4:7]
	v_mfma_f32_16x16x32_bf16 v[0:3], v[78:81], v[86:89], v[0:3]
	v_mfma_f32_16x16x32_bf16 v[12:15], v[74:77], v[66:69], v[12:15]
	v_mfma_f32_16x16x32_bf16 v[8:11], v[82:85], v[66:69], v[8:11]
	v_mfma_f32_16x16x32_bf16 v[4:7], v[74:77], v[90:93], v[4:7]
	v_mfma_f32_16x16x32_bf16 v[0:3], v[82:85], v[90:93], v[0:3]
	s_waitcnt vmcnt(8)
	ds_read_b128 v[62:65], v112 offset:8192
	ds_read_b128 v[66:69], v112 offset:8256
	ds_read_b128 v[70:73], v112 offset:10240
	ds_read_b128 v[74:77], v112 offset:10304
	ds_read_b128 v[78:81], v112 offset:12288
	ds_read_b128 v[82:85], v112 offset:12352
	ds_read_b128 v[86:89], v112 offset:14336
	ds_read_b128 v[90:93], v112 offset:14400
	s_waitcnt lgkmcnt(0)
	s_add_i32 m0, s100, 7040
	s_nop 0
	global_load_lds_dwordx4 v[94:95], off offset:1152
	s_add_i32 m0, s100, 8064
	s_nop 0
	global_load_lds_dwordx4 v[96:97], off offset:1152
	s_add_i32 m0, s100, 9088
	s_nop 0
	global_load_lds_dwordx4 v[98:99], off offset:1152
	s_add_i32 m0, s100, 10112
	s_nop 0
	global_load_lds_dwordx4 v[100:101], off offset:1152
	s_add_i32 m0, s100, 11136
	s_nop 0
	global_load_lds_dwordx4 v[102:103], off offset:1152
	s_add_i32 m0, s100, 12160
	s_nop 0
	global_load_lds_dwordx4 v[104:105], off offset:1152
	s_add_i32 m0, s100, 13184
	s_nop 0
	global_load_lds_dwordx4 v[106:107], off offset:1152
	s_add_i32 m0, s100, 14208
	s_nop 0
	global_load_lds_dwordx4 v[108:109], off offset:1152
	v_mfma_f32_16x16x32_bf16 v[12:15], v[70:73], v[62:65], v[12:15]
	v_mfma_f32_16x16x32_bf16 v[8:11], v[78:81], v[62:65], v[8:11]
	v_mfma_f32_16x16x32_bf16 v[4:7], v[70:73], v[86:89], v[4:7]
	v_mfma_f32_16x16x32_bf16 v[0:3], v[78:81], v[86:89], v[0:3]
	v_mfma_f32_16x16x32_bf16 v[12:15], v[74:77], v[66:69], v[12:15]
	v_mfma_f32_16x16x32_bf16 v[8:11], v[82:85], v[66:69], v[8:11]
	v_mfma_f32_16x16x32_bf16 v[4:7], v[74:77], v[90:93], v[4:7]
	v_mfma_f32_16x16x32_bf16 v[0:3], v[82:85], v[90:93], v[0:3]
	s_waitcnt vmcnt(8)
	ds_read_b128 v[62:65], v112
	ds_read_b128 v[66:69], v112 offset:64
	ds_read_b128 v[70:73], v112 offset:2048
	ds_read_b128 v[74:77], v112 offset:2112
	ds_read_b128 v[78:81], v112 offset:4096
	ds_read_b128 v[82:85], v112 offset:4160
	ds_read_b128 v[86:89], v112 offset:6144
	ds_read_b128 v[90:93], v112 offset:6208
	s_waitcnt lgkmcnt(0)
	s_add_i32 m0, s100, -1280
	s_nop 0
	global_load_lds_dwordx4 v[94:95], off offset:1280
	s_add_i32 m0, s100, -256
	s_nop 0
	global_load_lds_dwordx4 v[96:97], off offset:1280
	s_add_i32 m0, s100, 768
	s_nop 0
	global_load_lds_dwordx4 v[98:99], off offset:1280
	s_add_i32 m0, s100, 1792
	s_nop 0
	global_load_lds_dwordx4 v[100:101], off offset:1280
	s_add_i32 m0, s100, 2816
	s_nop 0
	global_load_lds_dwordx4 v[102:103], off offset:1280
	s_add_i32 m0, s100, 3840
	s_nop 0
	global_load_lds_dwordx4 v[104:105], off offset:1280
	s_add_i32 m0, s100, 4864
	s_nop 0
	global_load_lds_dwordx4 v[106:107], off offset:1280
	s_add_i32 m0, s100, 5888
	s_nop 0
	global_load_lds_dwordx4 v[108:109], off offset:1280
	v_mfma_f32_16x16x32_bf16 v[12:15], v[70:73], v[62:65], v[12:15]
	v_mfma_f32_16x16x32_bf16 v[8:11], v[78:81], v[62:65], v[8:11]
	v_mfma_f32_16x16x32_bf16 v[4:7], v[70:73], v[86:89], v[4:7]
	v_mfma_f32_16x16x32_bf16 v[0:3], v[78:81], v[86:89], v[0:3]
	v_mfma_f32_16x16x32_bf16 v[12:15], v[74:77], v[66:69], v[12:15]
	v_mfma_f32_16x16x32_bf16 v[8:11], v[82:85], v[66:69], v[8:11]
	v_mfma_f32_16x16x32_bf16 v[4:7], v[74:77], v[90:93], v[4:7]
	v_mfma_f32_16x16x32_bf16 v[0:3], v[82:85], v[90:93], v[0:3]
	s_waitcnt vmcnt(8)
	ds_read_b128 v[62:65], v112 offset:8192
	ds_read_b128 v[66:69], v112 offset:8256
	ds_read_b128 v[70:73], v112 offset:10240
	ds_read_b128 v[74:77], v112 offset:10304
	ds_read_b128 v[78:81], v112 offset:12288
	ds_read_b128 v[82:85], v112 offset:12352
	ds_read_b128 v[86:89], v112 offset:14336
	ds_read_b128 v[90:93], v112 offset:14400
	s_waitcnt lgkmcnt(0)
	s_add_i32 m0, s100, 6784
	s_nop 0
	global_load_lds_dwordx4 v[94:95], off offset:1408
	s_add_i32 m0, s100, 7808
	s_nop 0
	global_load_lds_dwordx4 v[96:97], off offset:1408
	s_add_i32 m0, s100, 8832
	s_nop 0
	global_load_lds_dwordx4 v[98:99], off offset:1408
	s_add_i32 m0, s100, 9856
	s_nop 0
	global_load_lds_dwordx4 v[100:101], off offset:1408
	s_add_i32 m0, s100, 10880
	s_nop 0
	global_load_lds_dwordx4 v[102:103], off offset:1408
	s_add_i32 m0, s100, 11904
	s_nop 0
	global_load_lds_dwordx4 v[104:105], off offset:1408
	s_add_i32 m0, s100, 12928
	s_nop 0
	global_load_lds_dwordx4 v[106:107], off offset:1408
	s_add_i32 m0, s100, 13952
	s_nop 0
	global_load_lds_dwordx4 v[108:109], off offset:1408
	v_mfma_f32_16x16x32_bf16 v[12:15], v[70:73], v[62:65], v[12:15]
	v_mfma_f32_16x16x32_bf16 v[8:11], v[78:81], v[62:65], v[8:11]
	v_mfma_f32_16x16x32_bf16 v[4:7], v[70:73], v[86:89], v[4:7]
	v_mfma_f32_16x16x32_bf16 v[0:3], v[78:81], v[86:89], v[0:3]
	v_mfma_f32_16x16x32_bf16 v[12:15], v[74:77], v[66:69], v[12:15]
	v_mfma_f32_16x16x32_bf16 v[8:11], v[82:85], v[66:69], v[8:11]
	v_mfma_f32_16x16x32_bf16 v[4:7], v[74:77], v[90:93], v[4:7]
	v_mfma_f32_16x16x32_bf16 v[0:3], v[82:85], v[90:93], v[0:3]
	s_waitcnt vmcnt(8)
	ds_read_b128 v[62:65], v112
	ds_read_b128 v[66:69], v112 offset:64
	ds_read_b128 v[70:73], v112 offset:2048
	ds_read_b128 v[74:77], v112 offset:2112
	ds_read_b128 v[78:81], v112 offset:4096
	ds_read_b128 v[82:85], v112 offset:4160
	ds_read_b128 v[86:89], v112 offset:6144
	ds_read_b128 v[90:93], v112 offset:6208
	s_waitcnt lgkmcnt(0)
	s_add_i32 m0, s100, -1536
	s_nop 0
	global_load_lds_dwordx4 v[94:95], off offset:1536
	s_add_i32 m0, s100, -512
	s_nop 0
	global_load_lds_dwordx4 v[96:97], off offset:1536
	s_add_i32 m0, s100, 512
	s_nop 0
	global_load_lds_dwordx4 v[98:99], off offset:1536
	s_add_i32 m0, s100, 1536
	s_nop 0
	global_load_lds_dwordx4 v[100:101], off offset:1536
	s_add_i32 m0, s100, 2560
	s_nop 0
	global_load_lds_dwordx4 v[102:103], off offset:1536
	s_add_i32 m0, s100, 3584
	s_nop 0
	global_load_lds_dwordx4 v[104:105], off offset:1536
	s_add_i32 m0, s100, 4608
	s_nop 0
	global_load_lds_dwordx4 v[106:107], off offset:1536
	s_add_i32 m0, s100, 5632
	s_nop 0
	global_load_lds_dwordx4 v[108:109], off offset:1536
	v_mfma_f32_16x16x32_bf16 v[12:15], v[70:73], v[62:65], v[12:15]
	v_mfma_f32_16x16x32_bf16 v[8:11], v[78:81], v[62:65], v[8:11]
	v_mfma_f32_16x16x32_bf16 v[4:7], v[70:73], v[86:89], v[4:7]
	v_mfma_f32_16x16x32_bf16 v[0:3], v[78:81], v[86:89], v[0:3]
	v_mfma_f32_16x16x32_bf16 v[12:15], v[74:77], v[66:69], v[12:15]
	v_mfma_f32_16x16x32_bf16 v[8:11], v[82:85], v[66:69], v[8:11]
	v_mfma_f32_16x16x32_bf16 v[4:7], v[74:77], v[90:93], v[4:7]
	v_mfma_f32_16x16x32_bf16 v[0:3], v[82:85], v[90:93], v[0:3]
	s_waitcnt vmcnt(8)
	ds_read_b128 v[62:65], v112 offset:8192
	ds_read_b128 v[66:69], v112 offset:8256
	ds_read_b128 v[70:73], v112 offset:10240
	ds_read_b128 v[74:77], v112 offset:10304
	ds_read_b128 v[78:81], v112 offset:12288
	ds_read_b128 v[82:85], v112 offset:12352
	ds_read_b128 v[86:89], v112 offset:14336
	ds_read_b128 v[90:93], v112 offset:14400
	s_waitcnt lgkmcnt(0)
	s_add_i32 m0, s100, 6528
	s_nop 0
	global_load_lds_dwordx4 v[94:95], off offset:1664
	s_add_i32 m0, s100, 7552
	s_nop 0
	global_load_lds_dwordx4 v[96:97], off offset:1664
	s_add_i32 m0, s100, 8576
	s_nop 0
	global_load_lds_dwordx4 v[98:99], off offset:1664
	s_add_i32 m0, s100, 9600
	s_nop 0
	global_load_lds_dwordx4 v[100:101], off offset:1664
	s_add_i32 m0, s100, 10624
	s_nop 0
	global_load_lds_dwordx4 v[102:103], off offset:1664
	s_add_i32 m0, s100, 11648
	s_nop 0
	global_load_lds_dwordx4 v[104:105], off offset:1664
	s_add_i32 m0, s100, 12672
	s_nop 0
	global_load_lds_dwordx4 v[106:107], off offset:1664
	s_add_i32 m0, s100, 13696
	s_nop 0
	global_load_lds_dwordx4 v[108:109], off offset:1664
	v_mfma_f32_16x16x32_bf16 v[12:15], v[70:73], v[62:65], v[12:15]
	v_mfma_f32_16x16x32_bf16 v[8:11], v[78:81], v[62:65], v[8:11]
	v_mfma_f32_16x16x32_bf16 v[4:7], v[70:73], v[86:89], v[4:7]
	v_mfma_f32_16x16x32_bf16 v[0:3], v[78:81], v[86:89], v[0:3]
	v_mfma_f32_16x16x32_bf16 v[12:15], v[74:77], v[66:69], v[12:15]
	v_mfma_f32_16x16x32_bf16 v[8:11], v[82:85], v[66:69], v[8:11]
	v_mfma_f32_16x16x32_bf16 v[4:7], v[74:77], v[90:93], v[4:7]
	v_mfma_f32_16x16x32_bf16 v[0:3], v[82:85], v[90:93], v[0:3]
	s_waitcnt vmcnt(8)
	ds_read_b128 v[62:65], v112
	ds_read_b128 v[66:69], v112 offset:64
	ds_read_b128 v[70:73], v112 offset:2048
	ds_read_b128 v[74:77], v112 offset:2112
	ds_read_b128 v[78:81], v112 offset:4096
	ds_read_b128 v[82:85], v112 offset:4160
	ds_read_b128 v[86:89], v112 offset:6144
	ds_read_b128 v[90:93], v112 offset:6208
	s_waitcnt lgkmcnt(0)
	s_add_i32 m0, s100, -1792
	s_nop 0
	global_load_lds_dwordx4 v[94:95], off offset:1792
	s_add_i32 m0, s100, -768
	s_nop 0
	global_load_lds_dwordx4 v[96:97], off offset:1792
	s_add_i32 m0, s100, 256
	s_nop 0
	global_load_lds_dwordx4 v[98:99], off offset:1792
	s_add_i32 m0, s100, 1280
	s_nop 0
	global_load_lds_dwordx4 v[100:101], off offset:1792
	s_add_i32 m0, s100, 2304
	s_nop 0
	global_load_lds_dwordx4 v[102:103], off offset:1792
	s_add_i32 m0, s100, 3328
	s_nop 0
	global_load_lds_dwordx4 v[104:105], off offset:1792
	s_add_i32 m0, s100, 4352
	s_nop 0
	global_load_lds_dwordx4 v[106:107], off offset:1792
	s_add_i32 m0, s100, 5376
	s_nop 0
	global_load_lds_dwordx4 v[108:109], off offset:1792
	v_mfma_f32_16x16x32_bf16 v[12:15], v[70:73], v[62:65], v[12:15]
	v_mfma_f32_16x16x32_bf16 v[8:11], v[78:81], v[62:65], v[8:11]
	v_mfma_f32_16x16x32_bf16 v[4:7], v[70:73], v[86:89], v[4:7]
	v_mfma_f32_16x16x32_bf16 v[0:3], v[78:81], v[86:89], v[0:3]
	v_mfma_f32_16x16x32_bf16 v[12:15], v[74:77], v[66:69], v[12:15]
	v_mfma_f32_16x16x32_bf16 v[8:11], v[82:85], v[66:69], v[8:11]
	v_mfma_f32_16x16x32_bf16 v[4:7], v[74:77], v[90:93], v[4:7]
	v_mfma_f32_16x16x32_bf16 v[0:3], v[82:85], v[90:93], v[0:3]
	s_waitcnt vmcnt(8)
	ds_read_b128 v[62:65], v112 offset:8192
	ds_read_b128 v[66:69], v112 offset:8256
	ds_read_b128 v[70:73], v112 offset:10240
	ds_read_b128 v[74:77], v112 offset:10304
	ds_read_b128 v[78:81], v112 offset:12288
	ds_read_b128 v[82:85], v112 offset:12352
	ds_read_b128 v[86:89], v112 offset:14336
	ds_read_b128 v[90:93], v112 offset:14400
	s_waitcnt lgkmcnt(0)
	s_add_i32 m0, s100, 6272
	s_nop 0
	global_load_lds_dwordx4 v[94:95], off offset:1920
	s_add_i32 m0, s100, 7296
	s_nop 0
	global_load_lds_dwordx4 v[96:97], off offset:1920
	s_add_i32 m0, s100, 8320
	s_nop 0
	global_load_lds_dwordx4 v[98:99], off offset:1920
	s_add_i32 m0, s100, 9344
	s_nop 0
	global_load_lds_dwordx4 v[100:101], off offset:1920
	s_add_i32 m0, s100, 10368
	s_nop 0
	global_load_lds_dwordx4 v[102:103], off offset:1920
	s_add_i32 m0, s100, 11392
	s_nop 0
	global_load_lds_dwordx4 v[104:105], off offset:1920
	s_add_i32 m0, s100, 12416
	s_nop 0
	global_load_lds_dwordx4 v[106:107], off offset:1920
	s_add_i32 m0, s100, 13440
	s_nop 0
	global_load_lds_dwordx4 v[108:109], off offset:1920
	v_mfma_f32_16x16x32_bf16 v[12:15], v[70:73], v[62:65], v[12:15]
	v_mfma_f32_16x16x32_bf16 v[8:11], v[78:81], v[62:65], v[8:11]
	v_mfma_f32_16x16x32_bf16 v[4:7], v[70:73], v[86:89], v[4:7]
	v_mfma_f32_16x16x32_bf16 v[0:3], v[78:81], v[86:89], v[0:3]
	v_mfma_f32_16x16x32_bf16 v[12:15], v[74:77], v[66:69], v[12:15]
	v_mfma_f32_16x16x32_bf16 v[8:11], v[82:85], v[66:69], v[8:11]
	v_mfma_f32_16x16x32_bf16 v[4:7], v[74:77], v[90:93], v[4:7]
	v_mfma_f32_16x16x32_bf16 v[0:3], v[82:85], v[90:93], v[0:3]
	s_waitcnt vmcnt(8)
	ds_read_b128 v[62:65], v112
	ds_read_b128 v[66:69], v112 offset:64
	ds_read_b128 v[70:73], v112 offset:2048
	ds_read_b128 v[74:77], v112 offset:2112
	ds_read_b128 v[78:81], v112 offset:4096
	ds_read_b128 v[82:85], v112 offset:4160
	ds_read_b128 v[86:89], v112 offset:6144
	ds_read_b128 v[90:93], v112 offset:6208
	s_waitcnt lgkmcnt(0)
	v_mfma_f32_16x16x32_bf16 v[12:15], v[70:73], v[62:65], v[12:15]
	v_mfma_f32_16x16x32_bf16 v[8:11], v[78:81], v[62:65], v[8:11]
	v_mfma_f32_16x16x32_bf16 v[4:7], v[70:73], v[86:89], v[4:7]
	v_mfma_f32_16x16x32_bf16 v[0:3], v[78:81], v[86:89], v[0:3]
	v_mfma_f32_16x16x32_bf16 v[12:15], v[74:77], v[66:69], v[12:15]
	v_mfma_f32_16x16x32_bf16 v[8:11], v[82:85], v[66:69], v[8:11]
	v_mfma_f32_16x16x32_bf16 v[4:7], v[74:77], v[90:93], v[4:7]
	v_mfma_f32_16x16x32_bf16 v[0:3], v[82:85], v[90:93], v[0:3]
	s_waitcnt vmcnt(0)
	ds_read_b128 v[62:65], v112 offset:8192
	ds_read_b128 v[66:69], v112 offset:8256
	ds_read_b128 v[70:73], v112 offset:10240
	ds_read_b128 v[74:77], v112 offset:10304
	ds_read_b128 v[78:81], v112 offset:12288
	ds_read_b128 v[82:85], v112 offset:12352
	ds_read_b128 v[86:89], v112 offset:14336
	ds_read_b128 v[90:93], v112 offset:14400
	s_waitcnt lgkmcnt(0)
	v_mfma_f32_16x16x32_bf16 v[12:15], v[70:73], v[62:65], v[12:15]
	v_mfma_f32_16x16x32_bf16 v[8:11], v[78:81], v[62:65], v[8:11]
	v_mfma_f32_16x16x32_bf16 v[4:7], v[70:73], v[86:89], v[4:7]
	v_mfma_f32_16x16x32_bf16 v[0:3], v[78:81], v[86:89], v[0:3]
	v_mfma_f32_16x16x32_bf16 v[12:15], v[74:77], v[66:69], v[12:15]
	v_mfma_f32_16x16x32_bf16 v[8:11], v[82:85], v[66:69], v[8:11]
	v_mfma_f32_16x16x32_bf16 v[4:7], v[74:77], v[90:93], v[4:7]
	v_mfma_f32_16x16x32_bf16 v[0:3], v[82:85], v[90:93], v[0:3]
	s_nop 1
	s_lshl_b32 s10, s8, 7
	s_and_b32 s10, s10, 0xf80
	v_or_b32_e32 v22, s10, v32
	s_mov_b32 s10, 0xc0135761
	v_pk_mul_f32 v[24:25], v[14:15], v[14:15]
	v_pk_mul_f32 v[26:27], v[12:13], v[12:13]
	v_mov_b64_e32 v[28:29], s[10:11]
	s_mov_b32 s10, 0x3dd2d3e7
	v_pk_fma_f32 v[26:27], v[26:27], s[10:11], v[28:29] op_sel_hi:[1,0,0] neg_lo:[1,0,0] neg_hi:[1,0,0]
	v_pk_fma_f32 v[24:25], v[24:25], s[10:11], v[28:29] op_sel_hi:[1,0,0] neg_lo:[1,0,0] neg_hi:[1,0,0]
	v_pk_mul_f32 v[26:27], v[12:13], v[26:27]
	v_pk_mul_f32 v[24:25], v[14:15], v[24:25]
	v_exp_f32_e32 v26, v26
	v_exp_f32_e32 v27, v27
	v_exp_f32_e32 v24, v24
	v_exp_f32_e32 v25, v25
	s_lshl_b32 s9, s8, 1
	v_pk_add_f32 v[26:27], v[26:27], 1.0 op_sel_hi:[1,0]
	s_andn2_b32 s9, s9, 63
	v_pk_add_f32 v[24:25], v[24:25], 1.0 op_sel_hi:[1,0]
	v_rcp_f32_e32 v26, v26
	v_rcp_f32_e32 v27, v27
	v_rcp_f32_e32 v24, v24
	v_rcp_f32_e32 v25, v25
	v_add_u32_e32 v20, s9, v33
	v_pk_mul_f32 v[12:13], v[12:13], v[26:27]
	v_pk_mul_f32 v[26:27], v[8:9], v[8:9]
	v_pk_mul_f32 v[14:15], v[14:15], v[24:25]
	v_pk_mul_f32 v[24:25], v[10:11], v[10:11]
	v_pk_fma_f32 v[26:27], v[26:27], s[10:11], v[28:29] op_sel_hi:[1,0,0] neg_lo:[1,0,0] neg_hi:[1,0,0]
	v_pk_fma_f32 v[24:25], v[24:25], s[10:11], v[28:29] op_sel_hi:[1,0,0] neg_lo:[1,0,0] neg_hi:[1,0,0]
	v_pk_mul_f32 v[26:27], v[8:9], v[26:27]
	v_pk_mul_f32 v[24:25], v[10:11], v[24:25]
	v_exp_f32_e32 v26, v26
	v_exp_f32_e32 v27, v27
	v_exp_f32_e32 v24, v24
	v_exp_f32_e32 v25, v25
	v_ashrrev_i32_e32 v21, 31, v20
	v_pk_add_f32 v[26:27], v[26:27], 1.0 op_sel_hi:[1,0]
	v_lshlrev_b32_e32 v148, 1, v22
	v_pk_add_f32 v[24:25], v[24:25], 1.0 op_sel_hi:[1,0]
	v_rcp_f32_e32 v26, v26
	v_rcp_f32_e32 v27, v27
	v_rcp_f32_e32 v24, v24
	v_rcp_f32_e32 v25, v25
	v_lshl_add_u64 v[22:23], v[16:17], 0, v[148:149]
	v_lshlrev_b64 v[30:31], 13, v[20:21]
	v_lshl_add_u64 v[30:31], v[22:23], 0, v[30:31]
	v_cvt_pk_bf16_f32 v12, v12, v13
	v_cvt_pk_bf16_f32 v13, v14, v15
	global_store_dwordx2 v[30:31], v[12:13], off
	v_pk_mul_f32 v[8:9], v[8:9], v[26:27]
	v_pk_mul_f32 v[10:11], v[10:11], v[24:25]
	v_pk_mul_f32 v[12:13], v[4:5], v[4:5]
	v_cvt_pk_bf16_f32 v8, v8, v9
	v_cvt_pk_bf16_f32 v9, v10, v11
	v_pk_mul_f32 v[10:11], v[6:7], v[6:7]
	v_pk_fma_f32 v[12:13], v[12:13], s[10:11], v[28:29] op_sel_hi:[1,0,0] neg_lo:[1,0,0] neg_hi:[1,0,0]
	v_pk_fma_f32 v[10:11], v[10:11], s[10:11], v[28:29] op_sel_hi:[1,0,0] neg_lo:[1,0,0] neg_hi:[1,0,0]
	v_pk_mul_f32 v[12:13], v[4:5], v[12:13]
	v_pk_mul_f32 v[10:11], v[6:7], v[10:11]
	v_exp_f32_e32 v12, v12
	v_exp_f32_e32 v13, v13
	v_exp_f32_e32 v10, v10
	v_exp_f32_e32 v11, v11
	global_store_dwordx2 v[30:31], v[8:9], off offset:32
	v_pk_add_f32 v[12:13], v[12:13], 1.0 op_sel_hi:[1,0]
	v_or_b32_e32 v8, 16, v20
	v_rcp_f32_e32 v12, v12
	v_rcp_f32_e32 v13, v13
	v_pk_add_f32 v[10:11], v[10:11], 1.0 op_sel_hi:[1,0]
	v_ashrrev_i32_e32 v9, 31, v8
	v_rcp_f32_e32 v10, v10
	v_rcp_f32_e32 v11, v11
	v_pk_mul_f32 v[4:5], v[4:5], v[12:13]
	v_pk_mul_f32 v[12:13], v[0:1], v[0:1]
	v_lshlrev_b64 v[8:9], 13, v[8:9]
	v_pk_mul_f32 v[6:7], v[6:7], v[10:11]
	v_pk_mul_f32 v[10:11], v[2:3], v[2:3]
	v_pk_fma_f32 v[12:13], v[12:13], s[10:11], v[28:29] op_sel_hi:[1,0,0] neg_lo:[1,0,0] neg_hi:[1,0,0]
	v_pk_fma_f32 v[10:11], v[10:11], s[10:11], v[28:29] op_sel_hi:[1,0,0] neg_lo:[1,0,0] neg_hi:[1,0,0]
	v_pk_mul_f32 v[12:13], v[0:1], v[12:13]
	v_pk_mul_f32 v[10:11], v[2:3], v[10:11]
	v_exp_f32_e32 v12, v12
	v_exp_f32_e32 v13, v13
	v_exp_f32_e32 v10, v10
	v_exp_f32_e32 v11, v11
	s_add_i32 s8, s8, s86
	v_pk_add_f32 v[12:13], v[12:13], 1.0 op_sel_hi:[1,0]
	s_add_i32 s5, s5, s11
	v_rcp_f32_e32 v12, v12
	v_rcp_f32_e32 v13, v13
	v_pk_add_f32 v[10:11], v[10:11], 1.0 op_sel_hi:[1,0]
	s_add_i32 s4, s4, s14
	v_rcp_f32_e32 v10, v10
	v_rcp_f32_e32 v11, v11
	v_lshl_add_u64 v[8:9], v[22:23], 0, v[8:9]
	v_pk_mul_f32 v[0:1], v[0:1], v[12:13]
	s_cmpk_gt_i32 s8, 0xff
	v_cvt_pk_bf16_f32 v4, v4, v5
	v_cvt_pk_bf16_f32 v5, v6, v7
	global_store_dwordx2 v[8:9], v[4:5], off
	v_pk_mul_f32 v[2:3], v[2:3], v[10:11]
	v_cvt_pk_bf16_f32 v0, v0, v1
	s_nop 0
	v_cvt_pk_bf16_f32 v1, v2, v3
	global_store_dwordx2 v[8:9], v[0:1], off offset:32
	s_cbranch_scc0 .LBB0_309

.LBB0_712:
	s_and_b32 s3, s1, 0xffffffc0
	v_add_u32_e32 v0, s3, v59
	s_lshl_b32 s3, s0, 11
	s_and_b32 s3, s3, 0x7c0000
	v_readlane_b32 s24, v245, 13
	v_lshl_or_b32 v148, v60, 11, s3
	v_readlane_b32 s25, v245, 14
	v_ashrrev_i32_e32 v1, 31, v0
	v_lshlrev_b64 v[0:1], 11, v[0:1]
	v_lshl_add_u64 v[30:31], s[24:25], 0, v[148:149]
	v_readlane_b32 s24, v245, 15
	v_readlane_b32 s25, v245, 16
	v_lshl_add_u64 v[20:21], s[88:89], 0, v[0:1]
	v_mov_b32_e32 v0, 0
	v_lshl_add_u64 v[32:33], s[24:25], 0, v[148:149]
	v_readlane_b32 s24, v245, 17
	v_readlane_b32 s25, v245, 18
	v_lshl_add_u64 v[22:23], s[10:11], 0, v[148:149]
	v_lshl_add_u64 v[24:25], s[14:15], 0, v[148:149]
	v_lshl_add_u64 v[34:35], s[24:25], 0, v[148:149]
	v_readlane_b32 s24, v245, 19
	v_readlane_b32 s25, v245, 20
	v_lshl_add_u64 v[26:27], s[20:21], 0, v[148:149]
	v_lshl_add_u64 v[28:29], s[22:23], 0, v[148:149]
	v_lshl_add_u64 v[36:37], s[24:25], 0, v[148:149]
	v_readlane_b32 s24, v245, 21
	v_readlane_b32 s25, v245, 22
	s_movk_i32 s3, 0xffe0
	v_mov_b32_e32 v1, v0
	v_lshl_add_u64 v[38:39], s[24:25], 0, v[148:149]
	v_readlane_b32 s24, v245, 23
	v_readlane_b32 s25, v245, 24
	v_mov_b32_e32 v2, v0
	v_mov_b32_e32 v3, v0
	v_lshl_add_u64 v[40:41], s[24:25], 0, v[148:149]
	v_readlane_b32 s24, v245, 25
	v_readlane_b32 s25, v245, 26
	v_mov_b32_e32 v4, v0
	v_mov_b32_e32 v5, v0
	v_lshl_add_u64 v[42:43], s[24:25], 0, v[148:149]
	v_readlane_b32 s24, v245, 27
	v_readlane_b32 s25, v245, 28
	v_mov_b32_e32 v6, v0
	v_mov_b32_e32 v7, v0
	v_lshl_add_u64 v[44:45], s[24:25], 0, v[148:149]
	v_readlane_b32 s24, v245, 29
	v_readlane_b32 s25, v245, 30
	v_mov_b32_e32 v8, v0
	v_mov_b32_e32 v9, v0
	v_lshl_add_u64 v[46:47], s[24:25], 0, v[148:149]
	v_readlane_b32 s24, v245, 31
	v_readlane_b32 s25, v245, 32
	v_mov_b32_e32 v10, v0
	v_mov_b32_e32 v11, v0
	v_lshl_add_u64 v[48:49], s[24:25], 0, v[148:149]
	v_readlane_b32 s24, v245, 40
	v_readlane_b32 s25, v245, 41
	v_mov_b32_e32 v12, v0
	v_mov_b32_e32 v13, v0
	v_lshl_add_u64 v[50:51], s[24:25], 0, v[148:149]
	v_readlane_b32 s24, v245, 33
	v_readlane_b32 s25, v245, 34
	v_mov_b32_e32 v14, v0
	v_mov_b32_e32 v15, v0
	v_lshl_add_u64 v[52:53], s[24:25], 0, v[148:149]
	v_lshl_add_u64 v[56:57], v[20:21], 0, v[18:19]
	v_add_co_u32_e32 v54, vcc, s7, v56
	s_nop 1
	v_addc_co_u32_e32 v55, vcc, 0, v57, vcc
	v_add_co_u32_e32 v56, vcc, s30, v56
	s_nop 1
	v_addc_co_u32_e32 v57, vcc, 0, v57, vcc
	v_lshl_add_u64 v[50:51], v[50:51], 0, v[18:19]
	v_lshl_add_u64 v[52:53], v[52:53], 0, v[18:19]
	v_and_b32_e32 v113, 63, v176
	v_lshrrev_b32_e32 v114, 3, v113
	v_and_b32_e32 v115, 15, v113
	v_sub_u32_e32 v114, v114, v115
	v_and_b32_e32 v116, 7, v113
	v_lshrrev_b32_e32 v117, 4, v113
	v_sub_u32_e32 v116, v116, v117
	v_lshlrev_b32_e32 v114, 11, v114
	v_lshl_add_u32 v110, v116, 4, v114
	v_ashrrev_i32_e32 v111, 31, v110
	v_lshl_add_u64 v[94:95], v[54:55], 0, v[110:111]
	s_nop 0
	v_add_co_u32_e32 v96, vcc, 0x4000, v94
	s_nop 1
	v_addc_co_u32_e32 v97, vcc, 0, v95, vcc
	v_lshl_add_u64 v[98:99], v[50:51], 0, v[110:111]
	s_nop 0
	v_add_co_u32_e32 v100, vcc, 0x4000, v98
	s_nop 1
	v_addc_co_u32_e32 v101, vcc, 0, v99, vcc
	v_lshl_add_u64 v[102:103], v[52:53], 0, v[110:111]
	s_nop 0
	v_add_co_u32_e32 v104, vcc, 0x4000, v102
	s_nop 1
	v_addc_co_u32_e32 v105, vcc, 0, v103, vcc
	v_lshl_add_u64 v[106:107], v[56:57], 0, v[110:111]
	s_nop 0
	v_add_co_u32_e32 v108, vcc, 0x4000, v106
	s_nop 1
	v_addc_co_u32_e32 v109, vcc, 0, v107, vcc
	v_lshrrev_b32_e32 v114, 3, v115
	v_and_b32_e32 v116, 7, v115
	v_lshlrev_b32_e32 v114, 10, v114
	v_lshl_add_u32 v114, v116, 7, v114
	v_lshl_add_u32 v112, v117, 4, v114
	v_lshrrev_b32_e32 v113, 6, v176
	s_nop 1
	v_readfirstlane_b32 s100, v113
	s_nop 3
	s_lshl_b32 s100, s100, 14
	s_add_i32 s100, s100, 0x800
	s_nop 0
	v_add_u32_e32 v112, s100, v112
	s_add_i32 m0, s100, 0
	s_nop 0
	global_load_lds_dwordx4 v[94:95], off
	s_add_i32 m0, s100, 1024
	s_nop 0
	global_load_lds_dwordx4 v[96:97], off
	s_add_i32 m0, s100, 2048
	s_nop 0
	global_load_lds_dwordx4 v[98:99], off
	s_add_i32 m0, s100, 3072
	s_nop 0
	global_load_lds_dwordx4 v[100:101], off
	s_add_i32 m0, s100, 4096
	s_nop 0
	global_load_lds_dwordx4 v[102:103], off
	s_add_i32 m0, s100, 5120
	s_nop 0
	global_load_lds_dwordx4 v[104:105], off
	s_add_i32 m0, s100, 6144
	s_nop 0
	global_load_lds_dwordx4 v[106:107], off
	s_add_i32 m0, s100, 7168
	s_nop 0
	global_load_lds_dwordx4 v[108:109], off
	s_add_i32 m0, s100, 8064
	s_nop 0
	global_load_lds_dwordx4 v[94:95], off offset:128
	s_add_i32 m0, s100, 9088
	s_nop 0
	global_load_lds_dwordx4 v[96:97], off offset:128
	s_add_i32 m0, s100, 10112
	s_nop 0
	global_load_lds_dwordx4 v[98:99], off offset:128
	s_add_i32 m0, s100, 11136
	s_nop 0
	global_load_lds_dwordx4 v[100:101], off offset:128
	s_add_i32 m0, s100, 12160
	s_nop 0
	global_load_lds_dwordx4 v[102:103], off offset:128
	s_add_i32 m0, s100, 13184
	s_nop 0
	global_load_lds_dwordx4 v[104:105], off offset:128
	s_add_i32 m0, s100, 14208
	s_nop 0
	global_load_lds_dwordx4 v[106:107], off offset:128
	s_add_i32 m0, s100, 15232
	s_nop 0
	global_load_lds_dwordx4 v[108:109], off offset:128
	s_waitcnt vmcnt(8)
	ds_read_b128 v[62:65], v112
	ds_read_b128 v[66:69], v112 offset:64
	ds_read_b128 v[70:73], v112 offset:2048
	ds_read_b128 v[74:77], v112 offset:2112
	ds_read_b128 v[78:81], v112 offset:4096
	ds_read_b128 v[82:85], v112 offset:4160
	ds_read_b128 v[86:89], v112 offset:6144
	ds_read_b128 v[90:93], v112 offset:6208
	s_waitcnt lgkmcnt(0)
	s_add_i32 m0, s100, -256
	s_nop 0
	global_load_lds_dwordx4 v[94:95], off offset:256
	s_add_i32 m0, s100, 768
	s_nop 0
	global_load_lds_dwordx4 v[96:97], off offset:256
	s_add_i32 m0, s100, 1792
	s_nop 0
	global_load_lds_dwordx4 v[98:99], off offset:256
	s_add_i32 m0, s100, 2816
	s_nop 0
	global_load_lds_dwordx4 v[100:101], off offset:256
	s_add_i32 m0, s100, 3840
	s_nop 0
	global_load_lds_dwordx4 v[102:103], off offset:256
	s_add_i32 m0, s100, 4864
	s_nop 0
	global_load_lds_dwordx4 v[104:105], off offset:256
	s_add_i32 m0, s100, 5888
	s_nop 0
	global_load_lds_dwordx4 v[106:107], off offset:256
	s_add_i32 m0, s100, 6912
	s_nop 0
	global_load_lds_dwordx4 v[108:109], off offset:256
	v_mfma_f32_16x16x32_bf16 v[12:15], v[70:73], v[62:65], v[12:15]
	v_mfma_f32_16x16x32_bf16 v[8:11], v[78:81], v[62:65], v[8:11]
	v_mfma_f32_16x16x32_bf16 v[4:7], v[70:73], v[86:89], v[4:7]
	v_mfma_f32_16x16x32_bf16 v[0:3], v[78:81], v[86:89], v[0:3]
	v_mfma_f32_16x16x32_bf16 v[12:15], v[74:77], v[66:69], v[12:15]
	v_mfma_f32_16x16x32_bf16 v[8:11], v[82:85], v[66:69], v[8:11]
	v_mfma_f32_16x16x32_bf16 v[4:7], v[74:77], v[90:93], v[4:7]
	v_mfma_f32_16x16x32_bf16 v[0:3], v[82:85], v[90:93], v[0:3]
	s_waitcnt vmcnt(8)
	ds_read_b128 v[62:65], v112 offset:8192
	ds_read_b128 v[66:69], v112 offset:8256
	ds_read_b128 v[70:73], v112 offset:10240
	ds_read_b128 v[74:77], v112 offset:10304
	ds_read_b128 v[78:81], v112 offset:12288
	ds_read_b128 v[82:85], v112 offset:12352
	ds_read_b128 v[86:89], v112 offset:14336
	ds_read_b128 v[90:93], v112 offset:14400
	s_waitcnt lgkmcnt(0)
	s_add_i32 m0, s100, 7808
	s_nop 0
	global_load_lds_dwordx4 v[94:95], off offset:384
	s_add_i32 m0, s100, 8832
	s_nop 0
	global_load_lds_dwordx4 v[96:97], off offset:384
	s_add_i32 m0, s100, 9856
	s_nop 0
	global_load_lds_dwordx4 v[98:99], off offset:384
	s_add_i32 m0, s100, 10880
	s_nop 0
	global_load_lds_dwordx4 v[100:101], off offset:384
	s_add_i32 m0, s100, 11904
	s_nop 0
	global_load_lds_dwordx4 v[102:103], off offset:384
	s_add_i32 m0, s100, 12928
	s_nop 0
	global_load_lds_dwordx4 v[104:105], off offset:384
	s_add_i32 m0, s100, 13952
	s_nop 0
	global_load_lds_dwordx4 v[106:107], off offset:384
	s_add_i32 m0, s100, 14976
	s_nop 0
	global_load_lds_dwordx4 v[108:109], off offset:384
	v_mfma_f32_16x16x32_bf16 v[12:15], v[70:73], v[62:65], v[12:15]
	v_mfma_f32_16x16x32_bf16 v[8:11], v[78:81], v[62:65], v[8:11]
	v_mfma_f32_16x16x32_bf16 v[4:7], v[70:73], v[86:89], v[4:7]
	v_mfma_f32_16x16x32_bf16 v[0:3], v[78:81], v[86:89], v[0:3]
	v_mfma_f32_16x16x32_bf16 v[12:15], v[74:77], v[66:69], v[12:15]
	v_mfma_f32_16x16x32_bf16 v[8:11], v[82:85], v[66:69], v[8:11]
	v_mfma_f32_16x16x32_bf16 v[4:7], v[74:77], v[90:93], v[4:7]
	v_mfma_f32_16x16x32_bf16 v[0:3], v[82:85], v[90:93], v[0:3]
	s_waitcnt vmcnt(8)
	ds_read_b128 v[62:65], v112
	ds_read_b128 v[66:69], v112 offset:64
	ds_read_b128 v[70:73], v112 offset:2048
	ds_read_b128 v[74:77], v112 offset:2112
	ds_read_b128 v[78:81], v112 offset:4096
	ds_read_b128 v[82:85], v112 offset:4160
	ds_read_b128 v[86:89], v112 offset:6144
	ds_read_b128 v[90:93], v112 offset:6208
	s_waitcnt lgkmcnt(0)
	s_add_i32 m0, s100, -512
	s_nop 0
	global_load_lds_dwordx4 v[94:95], off offset:512
	s_add_i32 m0, s100, 512
	s_nop 0
	global_load_lds_dwordx4 v[96:97], off offset:512
	s_add_i32 m0, s100, 1536
	s_nop 0
	global_load_lds_dwordx4 v[98:99], off offset:512
	s_add_i32 m0, s100, 2560
	s_nop 0
	global_load_lds_dwordx4 v[100:101], off offset:512
	s_add_i32 m0, s100, 3584
	s_nop 0
	global_load_lds_dwordx4 v[102:103], off offset:512
	s_add_i32 m0, s100, 4608
	s_nop 0
	global_load_lds_dwordx4 v[104:105], off offset:512
	s_add_i32 m0, s100, 5632
	s_nop 0
	global_load_lds_dwordx4 v[106:107], off offset:512
	s_add_i32 m0, s100, 6656
	s_nop 0
	global_load_lds_dwordx4 v[108:109], off offset:512
	v_mfma_f32_16x16x32_bf16 v[12:15], v[70:73], v[62:65], v[12:15]
	v_mfma_f32_16x16x32_bf16 v[8:11], v[78:81], v[62:65], v[8:11]
	v_mfma_f32_16x16x32_bf16 v[4:7], v[70:73], v[86:89], v[4:7]
	v_mfma_f32_16x16x32_bf16 v[0:3], v[78:81], v[86:89], v[0:3]
	v_mfma_f32_16x16x32_bf16 v[12:15], v[74:77], v[66:69], v[12:15]
	v_mfma_f32_16x16x32_bf16 v[8:11], v[82:85], v[66:69], v[8:11]
	v_mfma_f32_16x16x32_bf16 v[4:7], v[74:77], v[90:93], v[4:7]
	v_mfma_f32_16x16x32_bf16 v[0:3], v[82:85], v[90:93], v[0:3]
	s_waitcnt vmcnt(8)
	ds_read_b128 v[62:65], v112 offset:8192
	ds_read_b128 v[66:69], v112 offset:8256
	ds_read_b128 v[70:73], v112 offset:10240
	ds_read_b128 v[74:77], v112 offset:10304
	ds_read_b128 v[78:81], v112 offset:12288
	ds_read_b128 v[82:85], v112 offset:12352
	ds_read_b128 v[86:89], v112 offset:14336
	ds_read_b128 v[90:93], v112 offset:14400
	s_waitcnt lgkmcnt(0)
	s_add_i32 m0, s100, 7552
	s_nop 0
	global_load_lds_dwordx4 v[94:95], off offset:640
	s_add_i32 m0, s100, 8576
	s_nop 0
	global_load_lds_dwordx4 v[96:97], off offset:640
	s_add_i32 m0, s100, 9600
	s_nop 0
	global_load_lds_dwordx4 v[98:99], off offset:640
	s_add_i32 m0, s100, 10624
	s_nop 0
	global_load_lds_dwordx4 v[100:101], off offset:640
	s_add_i32 m0, s100, 11648
	s_nop 0
	global_load_lds_dwordx4 v[102:103], off offset:640
	s_add_i32 m0, s100, 12672
	s_nop 0
	global_load_lds_dwordx4 v[104:105], off offset:640
	s_add_i32 m0, s100, 13696
	s_nop 0
	global_load_lds_dwordx4 v[106:107], off offset:640
	s_add_i32 m0, s100, 14720
	s_nop 0
	global_load_lds_dwordx4 v[108:109], off offset:640
	v_mfma_f32_16x16x32_bf16 v[12:15], v[70:73], v[62:65], v[12:15]
	v_mfma_f32_16x16x32_bf16 v[8:11], v[78:81], v[62:65], v[8:11]
	v_mfma_f32_16x16x32_bf16 v[4:7], v[70:73], v[86:89], v[4:7]
	v_mfma_f32_16x16x32_bf16 v[0:3], v[78:81], v[86:89], v[0:3]
	v_mfma_f32_16x16x32_bf16 v[12:15], v[74:77], v[66:69], v[12:15]
	v_mfma_f32_16x16x32_bf16 v[8:11], v[82:85], v[66:69], v[8:11]
	v_mfma_f32_16x16x32_bf16 v[4:7], v[74:77], v[90:93], v[4:7]
	v_mfma_f32_16x16x32_bf16 v[0:3], v[82:85], v[90:93], v[0:3]
	s_waitcnt vmcnt(8)
	ds_read_b128 v[62:65], v112
	ds_read_b128 v[66:69], v112 offset:64
	ds_read_b128 v[70:73], v112 offset:2048
	ds_read_b128 v[74:77], v112 offset:2112
	ds_read_b128 v[78:81], v112 offset:4096
	ds_read_b128 v[82:85], v112 offset:4160
	ds_read_b128 v[86:89], v112 offset:6144
	ds_read_b128 v[90:93], v112 offset:6208
	s_waitcnt lgkmcnt(0)
	s_add_i32 m0, s100, -768
	s_nop 0
	global_load_lds_dwordx4 v[94:95], off offset:768
	s_add_i32 m0, s100, 256
	s_nop 0
	global_load_lds_dwordx4 v[96:97], off offset:768
	s_add_i32 m0, s100, 1280
	s_nop 0
	global_load_lds_dwordx4 v[98:99], off offset:768
	s_add_i32 m0, s100, 2304
	s_nop 0
	global_load_lds_dwordx4 v[100:101], off offset:768
	s_add_i32 m0, s100, 3328
	s_nop 0
	global_load_lds_dwordx4 v[102:103], off offset:768
	s_add_i32 m0, s100, 4352
	s_nop 0
	global_load_lds_dwordx4 v[104:105], off offset:768
	s_add_i32 m0, s100, 5376
	s_nop 0
	global_load_lds_dwordx4 v[106:107], off offset:768
	s_add_i32 m0, s100, 6400
	s_nop 0
	global_load_lds_dwordx4 v[108:109], off offset:768
	v_mfma_f32_16x16x32_bf16 v[12:15], v[70:73], v[62:65], v[12:15]
	v_mfma_f32_16x16x32_bf16 v[8:11], v[78:81], v[62:65], v[8:11]
	v_mfma_f32_16x16x32_bf16 v[4:7], v[70:73], v[86:89], v[4:7]
	v_mfma_f32_16x16x32_bf16 v[0:3], v[78:81], v[86:89], v[0:3]
	v_mfma_f32_16x16x32_bf16 v[12:15], v[74:77], v[66:69], v[12:15]
	v_mfma_f32_16x16x32_bf16 v[8:11], v[82:85], v[66:69], v[8:11]
	v_mfma_f32_16x16x32_bf16 v[4:7], v[74:77], v[90:93], v[4:7]
	v_mfma_f32_16x16x32_bf16 v[0:3], v[82:85], v[90:93], v[0:3]
	s_waitcnt vmcnt(8)
	ds_read_b128 v[62:65], v112 offset:8192
	ds_read_b128 v[66:69], v112 offset:8256
	ds_read_b128 v[70:73], v112 offset:10240
	ds_read_b128 v[74:77], v112 offset:10304
	ds_read_b128 v[78:81], v112 offset:12288
	ds_read_b128 v[82:85], v112 offset:12352
	ds_read_b128 v[86:89], v112 offset:14336
	ds_read_b128 v[90:93], v112 offset:14400
	s_waitcnt lgkmcnt(0)
	s_add_i32 m0, s100, 7296
	s_nop 0
	global_load_lds_dwordx4 v[94:95], off offset:896
	s_add_i32 m0, s100, 8320
	s_nop 0
	global_load_lds_dwordx4 v[96:97], off offset:896
	s_add_i32 m0, s100, 9344
	s_nop 0
	global_load_lds_dwordx4 v[98:99], off offset:896
	s_add_i32 m0, s100, 10368
	s_nop 0
	global_load_lds_dwordx4 v[100:101], off offset:896
	s_add_i32 m0, s100, 11392
	s_nop 0
	global_load_lds_dwordx4 v[102:103], off offset:896
	s_add_i32 m0, s100, 12416
	s_nop 0
	global_load_lds_dwordx4 v[104:105], off offset:896
	s_add_i32 m0, s100, 13440
	s_nop 0
	global_load_lds_dwordx4 v[106:107], off offset:896
	s_add_i32 m0, s100, 14464
	s_nop 0
	global_load_lds_dwordx4 v[108:109], off offset:896
	v_mfma_f32_16x16x32_bf16 v[12:15], v[70:73], v[62:65], v[12:15]
	v_mfma_f32_16x16x32_bf16 v[8:11], v[78:81], v[62:65], v[8:11]
	v_mfma_f32_16x16x32_bf16 v[4:7], v[70:73], v[86:89], v[4:7]
	v_mfma_f32_16x16x32_bf16 v[0:3], v[78:81], v[86:89], v[0:3]
	v_mfma_f32_16x16x32_bf16 v[12:15], v[74:77], v[66:69], v[12:15]
	v_mfma_f32_16x16x32_bf16 v[8:11], v[82:85], v[66:69], v[8:11]
	v_mfma_f32_16x16x32_bf16 v[4:7], v[74:77], v[90:93], v[4:7]
	v_mfma_f32_16x16x32_bf16 v[0:3], v[82:85], v[90:93], v[0:3]
	s_waitcnt vmcnt(8)
	ds_read_b128 v[62:65], v112
	ds_read_b128 v[66:69], v112 offset:64
	ds_read_b128 v[70:73], v112 offset:2048
	ds_read_b128 v[74:77], v112 offset:2112
	ds_read_b128 v[78:81], v112 offset:4096
	ds_read_b128 v[82:85], v112 offset:4160
	ds_read_b128 v[86:89], v112 offset:6144
	ds_read_b128 v[90:93], v112 offset:6208
	s_waitcnt lgkmcnt(0)
	s_add_i32 m0, s100, -1024
	s_nop 0
	global_load_lds_dwordx4 v[94:95], off offset:1024
	s_add_i32 m0, s100, 0
	s_nop 0
	global_load_lds_dwordx4 v[96:97], off offset:1024
	s_add_i32 m0, s100, 1024
	s_nop 0
	global_load_lds_dwordx4 v[98:99], off offset:1024
	s_add_i32 m0, s100, 2048
	s_nop 0
	global_load_lds_dwordx4 v[100:101], off offset:1024
	s_add_i32 m0, s100, 3072
	s_nop 0
	global_load_lds_dwordx4 v[102:103], off offset:1024
	s_add_i32 m0, s100, 4096
	s_nop 0
	global_load_lds_dwordx4 v[104:105], off offset:1024
	s_add_i32 m0, s100, 5120
	s_nop 0
	global_load_lds_dwordx4 v[106:107], off offset:1024
	s_add_i32 m0, s100, 6144
	s_nop 0
	global_load_lds_dwordx4 v[108:109], off offset:1024
	v_mfma_f32_16x16x32_bf16 v[12:15], v[70:73], v[62:65], v[12:15]
	v_mfma_f32_16x16x32_bf16 v[8:11], v[78:81], v[62:65], v[8:11]
	v_mfma_f32_16x16x32_bf16 v[4:7], v[70:73], v[86:89], v[4:7]
	v_mfma_f32_16x16x32_bf16 v[0:3], v[78:81], v[86:89], v[0:3]
	v_mfma_f32_16x16x32_bf16 v[12:15], v[74:77], v[66:69], v[12:15]
	v_mfma_f32_16x16x32_bf16 v[8:11], v[82:85], v[66:69], v[8:11]
	v_mfma_f32_16x16x32_bf16 v[4:7], v[74:77], v[90:93], v[4:7]
	v_mfma_f32_16x16x32_bf16 v[0:3], v[82:85], v[90:93], v[0:3]
	s_waitcnt vmcnt(8)
	ds_read_b128 v[62:65], v112 offset:8192
	ds_read_b128 v[66:69], v112 offset:8256
	ds_read_b128 v[70:73], v112 offset:10240
	ds_read_b128 v[74:77], v112 offset:10304
	ds_read_b128 v[78:81], v112 offset:12288
	ds_read_b128 v[82:85], v112 offset:12352
	ds_read_b128 v[86:89], v112 offset:14336
	ds_read_b128 v[90:93], v112 offset:14400
	s_waitcnt lgkmcnt(0)
	s_add_i32 m0, s100, 7040
	s_nop 0
	global_load_lds_dwordx4 v[94:95], off offset:1152
	s_add_i32 m0, s100, 8064
	s_nop 0
	global_load_lds_dwordx4 v[96:97], off offset:1152
	s_add_i32 m0, s100, 9088
	s_nop 0
	global_load_lds_dwordx4 v[98:99], off offset:1152
	s_add_i32 m0, s100, 10112
	s_nop 0
	global_load_lds_dwordx4 v[100:101], off offset:1152
	s_add_i32 m0, s100, 11136
	s_nop 0
	global_load_lds_dwordx4 v[102:103], off offset:1152
	s_add_i32 m0, s100, 12160
	s_nop 0
	global_load_lds_dwordx4 v[104:105], off offset:1152
	s_add_i32 m0, s100, 13184
	s_nop 0
	global_load_lds_dwordx4 v[106:107], off offset:1152
	s_add_i32 m0, s100, 14208
	s_nop 0
	global_load_lds_dwordx4 v[108:109], off offset:1152
	v_mfma_f32_16x16x32_bf16 v[12:15], v[70:73], v[62:65], v[12:15]
	v_mfma_f32_16x16x32_bf16 v[8:11], v[78:81], v[62:65], v[8:11]
	v_mfma_f32_16x16x32_bf16 v[4:7], v[70:73], v[86:89], v[4:7]
	v_mfma_f32_16x16x32_bf16 v[0:3], v[78:81], v[86:89], v[0:3]
	v_mfma_f32_16x16x32_bf16 v[12:15], v[74:77], v[66:69], v[12:15]
	v_mfma_f32_16x16x32_bf16 v[8:11], v[82:85], v[66:69], v[8:11]
	v_mfma_f32_16x16x32_bf16 v[4:7], v[74:77], v[90:93], v[4:7]
	v_mfma_f32_16x16x32_bf16 v[0:3], v[82:85], v[90:93], v[0:3]
	s_waitcnt vmcnt(8)
	ds_read_b128 v[62:65], v112
	ds_read_b128 v[66:69], v112 offset:64
	ds_read_b128 v[70:73], v112 offset:2048
	ds_read_b128 v[74:77], v112 offset:2112
	ds_read_b128 v[78:81], v112 offset:4096
	ds_read_b128 v[82:85], v112 offset:4160
	ds_read_b128 v[86:89], v112 offset:6144
	ds_read_b128 v[90:93], v112 offset:6208
	s_waitcnt lgkmcnt(0)
	s_add_i32 m0, s100, -1280
	s_nop 0
	global_load_lds_dwordx4 v[94:95], off offset:1280
	s_add_i32 m0, s100, -256
	s_nop 0
	global_load_lds_dwordx4 v[96:97], off offset:1280
	s_add_i32 m0, s100, 768
	s_nop 0
	global_load_lds_dwordx4 v[98:99], off offset:1280
	s_add_i32 m0, s100, 1792
	s_nop 0
	global_load_lds_dwordx4 v[100:101], off offset:1280
	s_add_i32 m0, s100, 2816
	s_nop 0
	global_load_lds_dwordx4 v[102:103], off offset:1280
	s_add_i32 m0, s100, 3840
	s_nop 0
	global_load_lds_dwordx4 v[104:105], off offset:1280
	s_add_i32 m0, s100, 4864
	s_nop 0
	global_load_lds_dwordx4 v[106:107], off offset:1280
	s_add_i32 m0, s100, 5888
	s_nop 0
	global_load_lds_dwordx4 v[108:109], off offset:1280
	v_mfma_f32_16x16x32_bf16 v[12:15], v[70:73], v[62:65], v[12:15]
	v_mfma_f32_16x16x32_bf16 v[8:11], v[78:81], v[62:65], v[8:11]
	v_mfma_f32_16x16x32_bf16 v[4:7], v[70:73], v[86:89], v[4:7]
	v_mfma_f32_16x16x32_bf16 v[0:3], v[78:81], v[86:89], v[0:3]
	v_mfma_f32_16x16x32_bf16 v[12:15], v[74:77], v[66:69], v[12:15]
	v_mfma_f32_16x16x32_bf16 v[8:11], v[82:85], v[66:69], v[8:11]
	v_mfma_f32_16x16x32_bf16 v[4:7], v[74:77], v[90:93], v[4:7]
	v_mfma_f32_16x16x32_bf16 v[0:3], v[82:85], v[90:93], v[0:3]
	s_waitcnt vmcnt(8)
	ds_read_b128 v[62:65], v112 offset:8192
	ds_read_b128 v[66:69], v112 offset:8256
	ds_read_b128 v[70:73], v112 offset:10240
	ds_read_b128 v[74:77], v112 offset:10304
	ds_read_b128 v[78:81], v112 offset:12288
	ds_read_b128 v[82:85], v112 offset:12352
	ds_read_b128 v[86:89], v112 offset:14336
	ds_read_b128 v[90:93], v112 offset:14400
	s_waitcnt lgkmcnt(0)
	s_add_i32 m0, s100, 6784
	s_nop 0
	global_load_lds_dwordx4 v[94:95], off offset:1408
	s_add_i32 m0, s100, 7808
	s_nop 0
	global_load_lds_dwordx4 v[96:97], off offset:1408
	s_add_i32 m0, s100, 8832
	s_nop 0
	global_load_lds_dwordx4 v[98:99], off offset:1408
	s_add_i32 m0, s100, 9856
	s_nop 0
	global_load_lds_dwordx4 v[100:101], off offset:1408
	s_add_i32 m0, s100, 10880
	s_nop 0
	global_load_lds_dwordx4 v[102:103], off offset:1408
	s_add_i32 m0, s100, 11904
	s_nop 0
	global_load_lds_dwordx4 v[104:105], off offset:1408
	s_add_i32 m0, s100, 12928
	s_nop 0
	global_load_lds_dwordx4 v[106:107], off offset:1408
	s_add_i32 m0, s100, 13952
	s_nop 0
	global_load_lds_dwordx4 v[108:109], off offset:1408
	v_mfma_f32_16x16x32_bf16 v[12:15], v[70:73], v[62:65], v[12:15]
	v_mfma_f32_16x16x32_bf16 v[8:11], v[78:81], v[62:65], v[8:11]
	v_mfma_f32_16x16x32_bf16 v[4:7], v[70:73], v[86:89], v[4:7]
	v_mfma_f32_16x16x32_bf16 v[0:3], v[78:81], v[86:89], v[0:3]
	v_mfma_f32_16x16x32_bf16 v[12:15], v[74:77], v[66:69], v[12:15]
	v_mfma_f32_16x16x32_bf16 v[8:11], v[82:85], v[66:69], v[8:11]
	v_mfma_f32_16x16x32_bf16 v[4:7], v[74:77], v[90:93], v[4:7]
	v_mfma_f32_16x16x32_bf16 v[0:3], v[82:85], v[90:93], v[0:3]
	s_waitcnt vmcnt(8)
	ds_read_b128 v[62:65], v112
	ds_read_b128 v[66:69], v112 offset:64
	ds_read_b128 v[70:73], v112 offset:2048
	ds_read_b128 v[74:77], v112 offset:2112
	ds_read_b128 v[78:81], v112 offset:4096
	ds_read_b128 v[82:85], v112 offset:4160
	ds_read_b128 v[86:89], v112 offset:6144
	ds_read_b128 v[90:93], v112 offset:6208
	s_waitcnt lgkmcnt(0)
	s_add_i32 m0, s100, -1536
	s_nop 0
	global_load_lds_dwordx4 v[94:95], off offset:1536
	s_add_i32 m0, s100, -512
	s_nop 0
	global_load_lds_dwordx4 v[96:97], off offset:1536
	s_add_i32 m0, s100, 512
	s_nop 0
	global_load_lds_dwordx4 v[98:99], off offset:1536
	s_add_i32 m0, s100, 1536
	s_nop 0
	global_load_lds_dwordx4 v[100:101], off offset:1536
	s_add_i32 m0, s100, 2560
	s_nop 0
	global_load_lds_dwordx4 v[102:103], off offset:1536
	s_add_i32 m0, s100, 3584
	s_nop 0
	global_load_lds_dwordx4 v[104:105], off offset:1536
	s_add_i32 m0, s100, 4608
	s_nop 0
	global_load_lds_dwordx4 v[106:107], off offset:1536
	s_add_i32 m0, s100, 5632
	s_nop 0
	global_load_lds_dwordx4 v[108:109], off offset:1536
	v_mfma_f32_16x16x32_bf16 v[12:15], v[70:73], v[62:65], v[12:15]
	v_mfma_f32_16x16x32_bf16 v[8:11], v[78:81], v[62:65], v[8:11]
	v_mfma_f32_16x16x32_bf16 v[4:7], v[70:73], v[86:89], v[4:7]
	v_mfma_f32_16x16x32_bf16 v[0:3], v[78:81], v[86:89], v[0:3]
	v_mfma_f32_16x16x32_bf16 v[12:15], v[74:77], v[66:69], v[12:15]
	v_mfma_f32_16x16x32_bf16 v[8:11], v[82:85], v[66:69], v[8:11]
	v_mfma_f32_16x16x32_bf16 v[4:7], v[74:77], v[90:93], v[4:7]
	v_mfma_f32_16x16x32_bf16 v[0:3], v[82:85], v[90:93], v[0:3]
	s_waitcnt vmcnt(8)
	ds_read_b128 v[62:65], v112 offset:8192
	ds_read_b128 v[66:69], v112 offset:8256
	ds_read_b128 v[70:73], v112 offset:10240
	ds_read_b128 v[74:77], v112 offset:10304
	ds_read_b128 v[78:81], v112 offset:12288
	ds_read_b128 v[82:85], v112 offset:12352
	ds_read_b128 v[86:89], v112 offset:14336
	ds_read_b128 v[90:93], v112 offset:14400
	s_waitcnt lgkmcnt(0)
	s_add_i32 m0, s100, 6528
	s_nop 0
	global_load_lds_dwordx4 v[94:95], off offset:1664
	s_add_i32 m0, s100, 7552
	s_nop 0
	global_load_lds_dwordx4 v[96:97], off offset:1664
	s_add_i32 m0, s100, 8576
	s_nop 0
	global_load_lds_dwordx4 v[98:99], off offset:1664
	s_add_i32 m0, s100, 9600
	s_nop 0
	global_load_lds_dwordx4 v[100:101], off offset:1664
	s_add_i32 m0, s100, 10624
	s_nop 0
	global_load_lds_dwordx4 v[102:103], off offset:1664
	s_add_i32 m0, s100, 11648
	s_nop 0
	global_load_lds_dwordx4 v[104:105], off offset:1664
	s_add_i32 m0, s100, 12672
	s_nop 0
	global_load_lds_dwordx4 v[106:107], off offset:1664
	s_add_i32 m0, s100, 13696
	s_nop 0
	global_load_lds_dwordx4 v[108:109], off offset:1664
	v_mfma_f32_16x16x32_bf16 v[12:15], v[70:73], v[62:65], v[12:15]
	v_mfma_f32_16x16x32_bf16 v[8:11], v[78:81], v[62:65], v[8:11]
	v_mfma_f32_16x16x32_bf16 v[4:7], v[70:73], v[86:89], v[4:7]
	v_mfma_f32_16x16x32_bf16 v[0:3], v[78:81], v[86:89], v[0:3]
	v_mfma_f32_16x16x32_bf16 v[12:15], v[74:77], v[66:69], v[12:15]
	v_mfma_f32_16x16x32_bf16 v[8:11], v[82:85], v[66:69], v[8:11]
	v_mfma_f32_16x16x32_bf16 v[4:7], v[74:77], v[90:93], v[4:7]
	v_mfma_f32_16x16x32_bf16 v[0:3], v[82:85], v[90:93], v[0:3]
	s_waitcnt vmcnt(8)
	ds_read_b128 v[62:65], v112
	ds_read_b128 v[66:69], v112 offset:64
	ds_read_b128 v[70:73], v112 offset:2048
	ds_read_b128 v[74:77], v112 offset:2112
	ds_read_b128 v[78:81], v112 offset:4096
	ds_read_b128 v[82:85], v112 offset:4160
	ds_read_b128 v[86:89], v112 offset:6144
	ds_read_b128 v[90:93], v112 offset:6208
	s_waitcnt lgkmcnt(0)
	s_add_i32 m0, s100, -1792
	s_nop 0
	global_load_lds_dwordx4 v[94:95], off offset:1792
	s_add_i32 m0, s100, -768
	s_nop 0
	global_load_lds_dwordx4 v[96:97], off offset:1792
	s_add_i32 m0, s100, 256
	s_nop 0
	global_load_lds_dwordx4 v[98:99], off offset:1792
	s_add_i32 m0, s100, 1280
	s_nop 0
	global_load_lds_dwordx4 v[100:101], off offset:1792
	s_add_i32 m0, s100, 2304
	s_nop 0
	global_load_lds_dwordx4 v[102:103], off offset:1792
	s_add_i32 m0, s100, 3328
	s_nop 0
	global_load_lds_dwordx4 v[104:105], off offset:1792
	s_add_i32 m0, s100, 4352
	s_nop 0
	global_load_lds_dwordx4 v[106:107], off offset:1792
	s_add_i32 m0, s100, 5376
	s_nop 0
	global_load_lds_dwordx4 v[108:109], off offset:1792
	v_mfma_f32_16x16x32_bf16 v[12:15], v[70:73], v[62:65], v[12:15]
	v_mfma_f32_16x16x32_bf16 v[8:11], v[78:81], v[62:65], v[8:11]
	v_mfma_f32_16x16x32_bf16 v[4:7], v[70:73], v[86:89], v[4:7]
	v_mfma_f32_16x16x32_bf16 v[0:3], v[78:81], v[86:89], v[0:3]
	v_mfma_f32_16x16x32_bf16 v[12:15], v[74:77], v[66:69], v[12:15]
	v_mfma_f32_16x16x32_bf16 v[8:11], v[82:85], v[66:69], v[8:11]
	v_mfma_f32_16x16x32_bf16 v[4:7], v[74:77], v[90:93], v[4:7]
	v_mfma_f32_16x16x32_bf16 v[0:3], v[82:85], v[90:93], v[0:3]
	s_waitcnt vmcnt(8)
	ds_read_b128 v[62:65], v112 offset:8192
	ds_read_b128 v[66:69], v112 offset:8256
	ds_read_b128 v[70:73], v112 offset:10240
	ds_read_b128 v[74:77], v112 offset:10304
	ds_read_b128 v[78:81], v112 offset:12288
	ds_read_b128 v[82:85], v112 offset:12352
	ds_read_b128 v[86:89], v112 offset:14336
	ds_read_b128 v[90:93], v112 offset:14400
	s_waitcnt lgkmcnt(0)
	s_add_i32 m0, s100, 6272
	s_nop 0
	global_load_lds_dwordx4 v[94:95], off offset:1920
	s_add_i32 m0, s100, 7296
	s_nop 0
	global_load_lds_dwordx4 v[96:97], off offset:1920
	s_add_i32 m0, s100, 8320
	s_nop 0
	global_load_lds_dwordx4 v[98:99], off offset:1920
	s_add_i32 m0, s100, 9344
	s_nop 0
	global_load_lds_dwordx4 v[100:101], off offset:1920
	s_add_i32 m0, s100, 10368
	s_nop 0
	global_load_lds_dwordx4 v[102:103], off offset:1920
	s_add_i32 m0, s100, 11392
	s_nop 0
	global_load_lds_dwordx4 v[104:105], off offset:1920
	s_add_i32 m0, s100, 12416
	s_nop 0
	global_load_lds_dwordx4 v[106:107], off offset:1920
	s_add_i32 m0, s100, 13440
	s_nop 0
	global_load_lds_dwordx4 v[108:109], off offset:1920
	v_mfma_f32_16x16x32_bf16 v[12:15], v[70:73], v[62:65], v[12:15]
	v_mfma_f32_16x16x32_bf16 v[8:11], v[78:81], v[62:65], v[8:11]
	v_mfma_f32_16x16x32_bf16 v[4:7], v[70:73], v[86:89], v[4:7]
	v_mfma_f32_16x16x32_bf16 v[0:3], v[78:81], v[86:89], v[0:3]
	v_mfma_f32_16x16x32_bf16 v[12:15], v[74:77], v[66:69], v[12:15]
	v_mfma_f32_16x16x32_bf16 v[8:11], v[82:85], v[66:69], v[8:11]
	v_mfma_f32_16x16x32_bf16 v[4:7], v[74:77], v[90:93], v[4:7]
	v_mfma_f32_16x16x32_bf16 v[0:3], v[82:85], v[90:93], v[0:3]
	s_waitcnt vmcnt(8)
	ds_read_b128 v[62:65], v112
	ds_read_b128 v[66:69], v112 offset:64
	ds_read_b128 v[70:73], v112 offset:2048
	ds_read_b128 v[74:77], v112 offset:2112
	ds_read_b128 v[78:81], v112 offset:4096
	ds_read_b128 v[82:85], v112 offset:4160
	ds_read_b128 v[86:89], v112 offset:6144
	ds_read_b128 v[90:93], v112 offset:6208
	s_waitcnt lgkmcnt(0)
	v_mfma_f32_16x16x32_bf16 v[12:15], v[70:73], v[62:65], v[12:15]
	v_mfma_f32_16x16x32_bf16 v[8:11], v[78:81], v[62:65], v[8:11]
	v_mfma_f32_16x16x32_bf16 v[4:7], v[70:73], v[86:89], v[4:7]
	v_mfma_f32_16x16x32_bf16 v[0:3], v[78:81], v[86:89], v[0:3]
	v_mfma_f32_16x16x32_bf16 v[12:15], v[74:77], v[66:69], v[12:15]
	v_mfma_f32_16x16x32_bf16 v[8:11], v[82:85], v[66:69], v[8:11]
	v_mfma_f32_16x16x32_bf16 v[4:7], v[74:77], v[90:93], v[4:7]
	v_mfma_f32_16x16x32_bf16 v[0:3], v[82:85], v[90:93], v[0:3]
	s_waitcnt vmcnt(0)
	ds_read_b128 v[62:65], v112 offset:8192
	ds_read_b128 v[66:69], v112 offset:8256
	ds_read_b128 v[70:73], v112 offset:10240
	ds_read_b128 v[74:77], v112 offset:10304
	ds_read_b128 v[78:81], v112 offset:12288
	ds_read_b128 v[82:85], v112 offset:12352
	ds_read_b128 v[86:89], v112 offset:14336
	ds_read_b128 v[90:93], v112 offset:14400
	s_waitcnt lgkmcnt(0)
	v_mfma_f32_16x16x32_bf16 v[12:15], v[70:73], v[62:65], v[12:15]
	v_mfma_f32_16x16x32_bf16 v[8:11], v[78:81], v[62:65], v[8:11]
	v_mfma_f32_16x16x32_bf16 v[4:7], v[70:73], v[86:89], v[4:7]
	v_mfma_f32_16x16x32_bf16 v[0:3], v[78:81], v[86:89], v[0:3]
	v_mfma_f32_16x16x32_bf16 v[12:15], v[74:77], v[66:69], v[12:15]
	v_mfma_f32_16x16x32_bf16 v[8:11], v[82:85], v[66:69], v[8:11]
	v_mfma_f32_16x16x32_bf16 v[4:7], v[74:77], v[90:93], v[4:7]
	v_mfma_f32_16x16x32_bf16 v[0:3], v[82:85], v[90:93], v[0:3]
	s_nop 1
	s_lshl_b32 s3, s2, 1
	s_lshl_b32 s4, s2, 7
	s_andn2_b32 s3, s3, 63
	s_and_b32 s4, s4, 0xf80
	v_or_b32_e32 v22, s4, v58
	v_add_u32_e32 v20, s3, v59
	v_max_f32_e32 v8, v8, v8
	v_ashrrev_i32_e32 v21, 31, v20
	v_lshlrev_b32_e32 v148, 1, v22
	v_max_f32_e32 v8, 0, v8
	v_max_f32_e32 v9, v9, v9
	v_lshl_add_u64 v[22:23], v[16:17], 0, v[148:149]
	v_lshlrev_b64 v[24:25], 13, v[20:21]
	v_mul_f32_e32 v8, v8, v8
	v_max_f32_e32 v9, 0, v9
	v_max_f32_e32 v10, v10, v10
	v_max_f32_e32 v11, v11, v11
	v_lshl_add_u64 v[24:25], v[22:23], 0, v[24:25]
	v_mul_f32_e32 v9, v9, v9
	v_max_f32_e32 v10, 0, v10
	v_max_f32_e32 v11, 0, v11
	v_cvt_pk_bf16_f32 v8, v8, v9
	v_mul_f32_e32 v10, v10, v10
	v_mul_f32_e32 v11, v11, v11
	v_cvt_pk_bf16_f32 v9, v10, v11
	global_store_dwordx2 v[24:25], v[8:9], off offset:32
	v_or_b32_e32 v8, 16, v20
	v_max_f32_e32 v12, v12, v12
	v_max_f32_e32 v13, v13, v13
	v_ashrrev_i32_e32 v9, 31, v8
	v_max_f32_e32 v4, v4, v4
	v_max_f32_e32 v5, v5, v5
	v_max_f32_e32 v0, v0, v0
	v_max_f32_e32 v1, v1, v1
	v_max_f32_e32 v12, 0, v12
	v_max_f32_e32 v13, 0, v13
	v_max_f32_e32 v14, v14, v14
	v_max_f32_e32 v15, v15, v15
	v_lshlrev_b64 v[8:9], 13, v[8:9]
	v_max_f32_e32 v4, 0, v4
	v_max_f32_e32 v5, 0, v5
	v_max_f32_e32 v6, v6, v6
	v_max_f32_e32 v7, v7, v7
	v_max_f32_e32 v0, 0, v0
	v_max_f32_e32 v1, 0, v1
	v_max_f32_e32 v2, v2, v2
	v_max_f32_e32 v3, v3, v3
	s_add_i32 s2, s2, s86
	s_add_i32 s1, s1, s5
	s_add_i32 s0, s0, s8
	v_mul_f32_e32 v12, v12, v12
	v_mul_f32_e32 v13, v13, v13
	v_max_f32_e32 v14, 0, v14
	v_max_f32_e32 v15, 0, v15
	v_lshl_add_u64 v[8:9], v[22:23], 0, v[8:9]
	v_mul_f32_e32 v4, v4, v4
	v_mul_f32_e32 v5, v5, v5
	v_max_f32_e32 v6, 0, v6
	v_max_f32_e32 v7, 0, v7
	v_mul_f32_e32 v0, v0, v0
	v_mul_f32_e32 v1, v1, v1
	v_max_f32_e32 v2, 0, v2
	v_max_f32_e32 v3, 0, v3
	s_cmpk_gt_i32 s2, 0xff
	v_mul_f32_e32 v14, v14, v14
	v_mul_f32_e32 v15, v15, v15
	v_cvt_pk_bf16_f32 v12, v12, v13
	v_cvt_pk_bf16_f32 v13, v14, v15
	global_store_dwordx2 v[24:25], v[12:13], off
	v_mul_f32_e32 v6, v6, v6
	v_mul_f32_e32 v7, v7, v7
	v_cvt_pk_bf16_f32 v4, v4, v5
	v_cvt_pk_bf16_f32 v5, v6, v7
	global_store_dwordx2 v[8:9], v[4:5], off
	v_mul_f32_e32 v2, v2, v2
	v_mul_f32_e32 v3, v3, v3
	v_cvt_pk_bf16_f32 v0, v0, v1
	v_cvt_pk_bf16_f32 v1, v2, v3
	global_store_dwordx2 v[8:9], v[0:1], off offset:32
	s_cbranch_scc0 .LBB0_712
